# row quantisation loops (after FFN1-down, after w_out, input rmsnorm): next row prefetched into staging registers, norm weights loaded once
# speedup vs baseline: 1.0030x; 1.0030x over previous
.LBB0_206:
	s_cmpk_gt_i32 s15, 0x3fff
	v_lshlrev_b32_e32 v2, 5, v31
	s_cbranch_scc1 .LBB0_211
	v_mbcnt_hi_u32_b32 v3, -1, v166
	v_and_b32_e32 v1, 64, v3
	v_add_u32_e32 v4, 64, v1
	v_xor_b32_e32 v1, 1, v3
	v_cmp_lt_i32_e32 vcc, v1, v4
	v_xor_b32_e32 v5, 2, v3
	v_readlane_b32 s7, v251, 39
	v_cndmask_b32_e32 v1, v3, v1, vcc
	v_cmp_lt_i32_e32 vcc, v5, v4
	v_readlane_b32 s2, v251, 38
	s_ashr_i32 s3, s7, 31
	v_cndmask_b32_e32 v5, v3, v5, vcc
	v_lshlrev_b32_e32 v7, 2, v5
	v_xor_b32_e32 v5, 4, v3
	v_cmp_lt_i32_e32 vcc, v5, v4
	s_ashr_i32 s6, s2, 31
	s_add_u32 s2, s7, s2
	v_cndmask_b32_e32 v5, v3, v5, vcc
	v_lshlrev_b32_e32 v20, 2, v5
	v_xor_b32_e32 v5, 8, v3
	v_cmp_lt_i32_e32 vcc, v5, v4
	s_addc_u32 s3, s3, s6
	v_readlane_b32 s24, v251, 8
	v_cndmask_b32_e32 v5, v3, v5, vcc
	s_lshl_b64 s[6:7], s[2:3], 2
	v_readlane_b32 s30, v251, 14
	v_lshlrev_b32_e32 v21, 2, v5
	v_xor_b32_e32 v5, 16, v3
	v_readlane_b32 s25, v251, 9
	v_readlane_b32 s31, v251, 15
	s_add_u32 s24, s30, s6
	v_cmp_lt_i32_e32 vcc, v5, v4
	v_readlane_b32 s26, v251, 10
	v_readlane_b32 s27, v251, 11
	s_addc_u32 s25, s31, s7
	s_mov_b32 s8, s10
	s_ashr_i32 s9, s10, 31
	v_cndmask_b32_e32 v5, v3, v5, vcc
	s_lshl_b64 s[26:27], s[8:9], 2
	s_lshl_b64 s[6:7], s[2:3], 13
	v_lshlrev_b32_e32 v22, 2, v5
	v_xor_b32_e32 v5, 32, v3
	v_readlane_b32 s28, v251, 12
	v_readlane_b32 s29, v251, 13
	s_add_u32 s6, s48, s6
	v_cmp_lt_i32_e32 vcc, v5, v4
	s_addc_u32 s7, s49, s7
	s_lshl_b64 s[28:29], s[8:9], 13
	s_lshl_b64 s[2:3], s[2:3], 11
	v_cndmask_b32_e32 v3, v3, v5, vcc
	v_mov_b32_e32 v9, 0
	s_add_u32 s2, s30, s2
	v_lshlrev_b32_e32 v23, 2, v3
	v_mov_b32_e32 v3, v9
	s_addc_u32 s3, s31, s3
	v_or_b32_e32 v10, 0x1000, v2
	v_mov_b32_e32 v11, v9
	v_or_b32_e32 v12, 0x1800, v2
	v_mov_b32_e32 v13, v9
	v_lshl_add_u64 v[14:15], s[6:7], 0, v[2:3]
	s_mov_b64 s[6:7], 0x1000
	v_lshl_add_u64 v[16:17], s[2:3], 0, v[8:9]
	s_mov_b64 s[2:3], 0xa600400
	v_lshlrev_b32_e32 v1, 2, v1
	v_cmp_eq_u32_e64 s[0:1], 0, v31
	v_lshl_add_u64 v[4:5], s[52:53], 0, v[2:3]
	v_lshl_add_u64 v[10:11], s[52:53], 0, v[10:11]
	v_lshl_add_u64 v[12:13], s[52:53], 0, v[12:13]
	v_lshl_add_u64 v[14:15], v[14:15], 0, s[6:7]
	v_lshl_add_u64 v[16:17], v[16:17], 0, s[2:3]
	s_lshl_b64 s[30:31], s[8:9], 11
	s_mov_b32 s6, 0xda24260
	s_mov_b32 s7, 0x42fe0000
	s_mov_b32 s8, 0xc2fe0000
	v_mov_b32_e32 v3, 0x42fe0000
	s_mov_b32 s9, 0x40c0c00
	v_mov_b32_e32 v8, 0x358637bd
	s_mov_b32 s12, 0x800000
	v_mov_b32_e32 v24, 0x10000
	v_mov_b32_e32 v25, 0x20000
	v_mov_b32_e32 v26, 0x30000
	s_mov_b32 s14, s15
	global_load_dwordx4 v[128:131], v[4:5], off
	global_load_dwordx4 v[132:135], v[4:5], off offset:16
	global_load_dwordx4 v[136:139], v[4:5], off offset:2048
	global_load_dwordx4 v[140:143], v[4:5], off offset:2064
	global_load_dwordx4 v[144:147], v[10:11], off
	global_load_dwordx4 v[148:151], v[10:11], off offset:16
	global_load_dwordx4 v[152:155], v[12:13], off
	global_load_dwordx4 v[156:159], v[12:13], off offset:16
	global_load_dwordx4 v[96:99], v[14:15], off offset:-4096
	global_load_dwordx4 v[100:103], v[14:15], off offset:-4080
	global_load_dwordx4 v[104:107], v[14:15], off offset:-2048
	global_load_dwordx4 v[108:111], v[14:15], off offset:-2032
	global_load_dwordx4 v[112:115], v[14:15], off
	global_load_dwordx4 v[116:119], v[14:15], off offset:16
	global_load_dwordx4 v[120:123], v[14:15], off offset:2048
	global_load_dwordx4 v[124:127], v[14:15], off offset:2064
	s_waitcnt vmcnt(0)
	s_branch .LBB0_209

.LBB0_209:
	s_waitcnt vmcnt(4)
	v_mov_b32_e32 v32, v96
	v_mov_b32_e32 v33, v97
	v_mov_b32_e32 v34, v98
	v_mov_b32_e32 v35, v99
	v_mov_b32_e32 v40, v100
	v_mov_b32_e32 v41, v101
	v_mov_b32_e32 v42, v102
	v_mov_b32_e32 v43, v103
	v_mov_b32_e32 v48, v104
	v_mov_b32_e32 v49, v105
	v_mov_b32_e32 v50, v106
	v_mov_b32_e32 v51, v107
	v_mov_b32_e32 v56, v108
	v_mov_b32_e32 v57, v109
	v_mov_b32_e32 v58, v110
	v_mov_b32_e32 v59, v111
	v_mov_b32_e32 v64, v112
	v_mov_b32_e32 v65, v113
	v_mov_b32_e32 v66, v114
	v_mov_b32_e32 v67, v115
	v_mov_b32_e32 v72, v116
	v_mov_b32_e32 v73, v117
	v_mov_b32_e32 v74, v118
	v_mov_b32_e32 v75, v119
	v_mov_b32_e32 v80, v120
	v_mov_b32_e32 v81, v121
	v_mov_b32_e32 v82, v122
	v_mov_b32_e32 v83, v123
	v_mov_b32_e32 v84, v124
	v_mov_b32_e32 v85, v125
	v_mov_b32_e32 v86, v126
	v_mov_b32_e32 v87, v127
	v_mov_b32_e32 v36, v128
	v_mov_b32_e32 v37, v129
	v_mov_b32_e32 v38, v130
	v_mov_b32_e32 v39, v131
	v_mov_b32_e32 v44, v132
	v_mov_b32_e32 v45, v133
	v_mov_b32_e32 v46, v134
	v_mov_b32_e32 v47, v135
	v_mov_b32_e32 v52, v136
	v_mov_b32_e32 v53, v137
	v_mov_b32_e32 v54, v138
	v_mov_b32_e32 v55, v139
	v_mov_b32_e32 v60, v140
	v_mov_b32_e32 v61, v141
	v_mov_b32_e32 v62, v142
	v_mov_b32_e32 v63, v143
	v_mov_b32_e32 v68, v144
	v_mov_b32_e32 v69, v145
	v_mov_b32_e32 v70, v146
	v_mov_b32_e32 v71, v147
	v_mov_b32_e32 v76, v148
	v_mov_b32_e32 v77, v149
	v_mov_b32_e32 v78, v150
	v_mov_b32_e32 v79, v151
	v_mov_b32_e32 v88, v152
	v_mov_b32_e32 v89, v153
	v_mov_b32_e32 v90, v154
	v_mov_b32_e32 v91, v155
	v_mov_b32_e32 v92, v156
	v_mov_b32_e32 v93, v157
	v_mov_b32_e32 v94, v158
	v_mov_b32_e32 v95, v159
	s_add_i32 vcc_lo, s14, s10
	s_cmpk_gt_i32 vcc_lo, 0x3fff
	s_cbranch_scc1 .Lrq0_nopf
	v_lshl_add_u64 v[160:161], v[14:15], 0, s[28:29]
	global_load_dwordx4 v[96:99], v[160:161], off offset:-4096
	global_load_dwordx4 v[100:103], v[160:161], off offset:-4080
	global_load_dwordx4 v[104:107], v[160:161], off offset:-2048
	global_load_dwordx4 v[108:111], v[160:161], off offset:-2032
	global_load_dwordx4 v[112:115], v[160:161], off
	global_load_dwordx4 v[116:119], v[160:161], off offset:16
	global_load_dwordx4 v[120:123], v[160:161], off offset:2048
	global_load_dwordx4 v[124:127], v[160:161], off offset:2064
.Lrq0_nopf:
	v_mul_f32_e32 v27, v33, v33
	v_pk_mul_f32 v[38:39], v[34:35], v[38:39]
	v_pk_mul_f32 v[36:37], v[32:33], v[36:37]
	v_mul_f32_e32 v28, v34, v34
	v_pk_mul_f32 v[44:45], v[40:41], v[44:45]
	v_mul_f32_e32 v33, v49, v49
	v_mul_f32_e32 v34, v50, v50
	s_waitcnt lgkmcnt(0)
	v_mul_f32_e32 v29, v41, v41
	v_mul_f32_e32 v30, v43, v43
	v_pk_mul_f32 v[46:47], v[42:43], v[46:47]
	v_pk_mul_f32 v[54:55], v[50:51], v[54:55]
	v_pk_mul_f32 v[52:53], v[48:49], v[52:53]
	v_mul_f32_e32 v41, v57, v57
	v_mul_f32_e32 v49, v65, v65
	v_mul_f32_e32 v50, v66, v66
	v_fmac_f32_e32 v27, v32, v32
	v_fmac_f32_e32 v28, v35, v35
	v_fmac_f32_e32 v33, v48, v48
	v_fmac_f32_e32 v34, v51, v51
	v_max_f32_e64 v32, |v36|, |v44|
	v_max_f32_e64 v35, |v37|, |v45|
	v_mul_f32_e32 v43, v59, v59
	v_pk_mul_f32 v[60:61], v[56:57], v[60:61]
	v_mul_f32_e32 v57, v73, v73
	v_fmac_f32_e32 v29, v40, v40
	v_fmac_f32_e32 v30, v42, v42
	v_fmac_f32_e32 v41, v56, v56
	v_fmac_f32_e32 v49, v64, v64
	v_fmac_f32_e32 v50, v67, v67
	v_max_f32_e64 v40, |v38|, |v46|
	v_max_f32_e64 v42, |v39|, |v47|
	v_add_f32_e32 v27, v27, v28
	v_add_f32_e32 v28, v33, v34
	v_max3_f32 v32, v32, 0, v35
	v_pk_mul_f32 v[62:63], v[58:59], v[62:63]
	v_pk_mul_f32 v[70:71], v[66:67], v[70:71]
	v_pk_mul_f32 v[68:69], v[64:65], v[68:69]
	v_mul_f32_e32 v59, v75, v75
	v_mul_f32_e32 v65, v81, v81
	v_mul_f32_e32 v66, v82, v82
	v_fmac_f32_e32 v43, v58, v58
	v_fmac_f32_e32 v57, v72, v72
	v_max_f32_e64 v48, |v52|, |v60|
	v_max_f32_e64 v51, |v53|, |v61|
	v_add_f32_e32 v33, v49, v50
	v_max3_f32 v32, v32, v40, v42
	v_add_f32_e32 v27, v29, v27
	v_add_f32_e32 v28, v41, v28
	v_pk_mul_f32 v[76:77], v[72:73], v[76:77]
	v_mul_f32_e32 v73, v85, v85
	v_fmac_f32_e32 v59, v74, v74
	v_fmac_f32_e32 v65, v80, v80
	v_fmac_f32_e32 v66, v83, v83
	v_max_f32_e64 v56, |v54|, |v62|
	v_max_f32_e64 v58, |v55|, |v63|
	v_add_f32_e32 v29, v57, v33
	v_max3_f32 v32, v32, v48, v51
	v_add_f32_e32 v27, v30, v27
	v_add_f32_e32 v28, v43, v28
	v_pk_mul_f32 v[18:19], v[74:75], v[78:79]
	v_fmac_f32_e32 v73, v84, v84
	v_max_f32_e64 v64, |v68|, |v76|
	v_max_f32_e64 v67, |v69|, |v77|
	v_add_f32_e32 v34, v65, v66
	v_add_f32_e32 v29, v59, v29
	v_add_f32_e32 v27, v27, v28
	v_max3_f32 v28, v32, v56, v58
	v_add_f32_e32 v49, v73, v34
	v_add_f32_e32 v27, v27, v29
	v_max3_f32 v28, v28, v64, v67
	v_max_f32_e64 v29, |v70|, |v18|
	v_max_f32_e64 v30, |v71|, |v19|
	v_pk_mul_f32 v[34:35], v[80:81], v[88:89]
	v_pk_mul_f32 v[42:43], v[84:85], v[92:93]
	v_max3_f32 v28, v28, v29, v30
	v_pk_mul_f32 v[32:33], v[82:83], v[90:91]
	v_pk_mul_f32 v[40:41], v[86:87], v[94:95]
	v_max_f32_e64 v29, |v34|, |v42|
	v_max_f32_e64 v30, |v35|, |v43|
	v_max3_f32 v28, v28, v29, v30
	v_max_f32_e64 v29, |v32|, |v40|
	v_max_f32_e64 v30, |v33|, |v41|
	v_max3_f32 v28, v28, v29, v30
	ds_bpermute_b32 v29, v1, v28
	v_mul_f32_e32 v75, v87, v87
	v_fmac_f32_e32 v75, v86, v86
	v_add_f32_e32 v30, v75, v49
	v_add_f32_e32 v27, v27, v30
	s_waitcnt lgkmcnt(0)
	v_max_f32_e32 v29, v29, v29
	v_max_f32_e32 v28, v28, v29
	ds_bpermute_b32 v29, v7, v28
	ds_bpermute_b32 v30, v1, v27
	s_waitcnt lgkmcnt(1)
	v_max_f32_e32 v29, v29, v29
	v_max_f32_e32 v28, v28, v29
	ds_bpermute_b32 v29, v20, v28
	s_waitcnt lgkmcnt(1)
	v_add_f32_e32 v27, v27, v30
	ds_bpermute_b32 v30, v7, v27
	s_waitcnt lgkmcnt(1)
	v_max_f32_e32 v29, v29, v29
	v_max_f32_e32 v28, v28, v29
	ds_bpermute_b32 v29, v21, v28
	s_waitcnt lgkmcnt(1)
	v_add_f32_e32 v27, v27, v30
	ds_bpermute_b32 v30, v20, v27
	s_waitcnt lgkmcnt(1)
	v_max_f32_e32 v29, v29, v29
	v_max_f32_e32 v28, v28, v29
	s_waitcnt lgkmcnt(0)
	v_add_f32_e32 v27, v27, v30
	ds_bpermute_b32 v29, v22, v28
	ds_bpermute_b32 v30, v21, v27
	s_waitcnt lgkmcnt(1)
	v_max_f32_e32 v29, v29, v29
	s_waitcnt lgkmcnt(0)
	v_add_f32_e32 v27, v27, v30
	v_max_f32_e32 v29, v28, v29
	ds_bpermute_b32 v30, v22, v27
	ds_bpermute_b32 v48, v23, v29
	s_waitcnt lgkmcnt(1)
	v_add_f32_e32 v28, v27, v30
	s_waitcnt lgkmcnt(0)
	v_max3_f32 v27, v29, v48, s6
	v_div_scale_f32 v30, s[2:3], v27, v27, s7
	v_rcp_f32_e32 v48, v30
	v_div_scale_f32 v49, vcc, s7, v27, s7
	ds_bpermute_b32 v29, v23, v28
	v_fma_f32 v50, -v30, v48, 1.0
	v_fmac_f32_e32 v48, v50, v48
	v_mul_f32_e32 v50, v49, v48
	v_fma_f32 v51, -v30, v50, v49
	v_fmac_f32_e32 v50, v51, v48
	v_fma_f32 v30, -v30, v50, v49
	v_div_fmas_f32 v30, v30, v48, v50
	v_div_fixup_f32 v30, v30, v27, s7
	v_mul_f32_e32 v37, v30, v37
	v_mul_f32_e32 v36, v30, v36
	v_mul_f32_e32 v38, v30, v38
	v_mul_f32_e32 v39, v30, v39
	v_med3_f32 v37, v37, s8, v3
	v_med3_f32 v36, v36, s8, v3
	v_rndne_f32_e32 v37, v37
	v_med3_f32 v38, v38, s8, v3
	v_med3_f32 v39, v39, s8, v3
	v_rndne_f32_e32 v36, v36
	v_cvt_i32_f32_e32 v37, v37
	v_rndne_f32_e32 v38, v38
	v_rndne_f32_e32 v39, v39
	v_cvt_i32_f32_e32 v36, v36
	v_cvt_i32_f32_sdwa v38, v38 dst_sel:WORD_1 dst_unused:UNUSED_PAD src0_sel:DWORD
	v_cvt_i32_f32_e32 v39, v39
	v_lshlrev_b32_e32 v37, 8, v37
	v_and_b32_e32 v37, 0xff00, v37
	v_and_b32_e32 v38, 0xff0000, v38
	v_perm_b32 v36, v39, v36, s9
	v_or3_b32 v36, v36, v37, v38
	v_mul_f32_e32 v38, v30, v45
	v_mul_f32_e32 v37, v30, v44
	v_mul_f32_e32 v39, v30, v46
	v_mul_f32_e32 v44, v30, v47
	v_med3_f32 v38, v38, s8, v3
	v_med3_f32 v37, v37, s8, v3
	v_rndne_f32_e32 v38, v38
	v_med3_f32 v39, v39, s8, v3
	v_med3_f32 v44, v44, s8, v3
	v_rndne_f32_e32 v37, v37
	v_cvt_i32_f32_e32 v38, v38
	v_rndne_f32_e32 v39, v39
	v_rndne_f32_e32 v44, v44
	v_cvt_i32_f32_e32 v37, v37
	v_cvt_i32_f32_sdwa v39, v39 dst_sel:WORD_1 dst_unused:UNUSED_PAD src0_sel:DWORD
	v_cvt_i32_f32_e32 v44, v44
	v_lshlrev_b32_e32 v38, 8, v38
	v_and_b32_e32 v38, 0xff00, v38
	v_and_b32_e32 v39, 0xff0000, v39
	v_perm_b32 v37, v44, v37, s9
	v_or3_b32 v37, v37, v38, v39
	global_store_dwordx2 v[16:17], v[36:37], off offset:-1024
	v_mul_f32_e32 v37, v30, v53
	v_mul_f32_e32 v36, v30, v52
	v_mul_f32_e32 v38, v30, v54
	v_mul_f32_e32 v39, v30, v55
	v_med3_f32 v37, v37, s8, v3
	v_med3_f32 v36, v36, s8, v3
	v_rndne_f32_e32 v37, v37
	v_med3_f32 v38, v38, s8, v3
	v_med3_f32 v39, v39, s8, v3
	v_rndne_f32_e32 v36, v36
	v_cvt_i32_f32_e32 v37, v37
	v_rndne_f32_e32 v38, v38
	v_rndne_f32_e32 v39, v39
	v_cvt_i32_f32_e32 v36, v36
	v_cvt_i32_f32_sdwa v38, v38 dst_sel:WORD_1 dst_unused:UNUSED_PAD src0_sel:DWORD
	v_cvt_i32_f32_e32 v39, v39
	v_lshlrev_b32_e32 v37, 8, v37
	v_and_b32_e32 v37, 0xff00, v37
	v_and_b32_e32 v38, 0xff0000, v38
	v_perm_b32 v36, v39, v36, s9
	v_or3_b32 v36, v36, v37, v38
	v_mul_f32_e32 v38, v30, v61
	v_mul_f32_e32 v37, v30, v60
	v_mul_f32_e32 v39, v30, v62
	v_mul_f32_e32 v44, v30, v63
	v_med3_f32 v38, v38, s8, v3
	v_med3_f32 v37, v37, s8, v3
	v_rndne_f32_e32 v38, v38
	v_med3_f32 v39, v39, s8, v3
	v_med3_f32 v44, v44, s8, v3
	v_rndne_f32_e32 v37, v37
	v_cvt_i32_f32_e32 v38, v38
	v_rndne_f32_e32 v39, v39
	v_rndne_f32_e32 v44, v44
	v_cvt_i32_f32_e32 v37, v37
	v_cvt_i32_f32_sdwa v39, v39 dst_sel:WORD_1 dst_unused:UNUSED_PAD src0_sel:DWORD
	v_cvt_i32_f32_e32 v44, v44
	v_lshlrev_b32_e32 v38, 8, v38
	v_and_b32_e32 v38, 0xff00, v38
	v_and_b32_e32 v39, 0xff0000, v39
	v_perm_b32 v37, v44, v37, s9
	v_or3_b32 v37, v37, v38, v39
	global_store_dwordx2 v[16:17], v[36:37], off offset:-512
	v_mul_f32_e32 v37, v30, v69
	v_mul_f32_e32 v36, v30, v68
	v_mul_f32_e32 v38, v30, v70
	v_mul_f32_e32 v39, v30, v71
	v_med3_f32 v37, v37, s8, v3
	v_med3_f32 v36, v36, s8, v3
	v_rndne_f32_e32 v37, v37
	v_med3_f32 v38, v38, s8, v3
	v_med3_f32 v39, v39, s8, v3
	v_rndne_f32_e32 v36, v36
	v_cvt_i32_f32_e32 v37, v37
	v_rndne_f32_e32 v38, v38
	v_rndne_f32_e32 v39, v39
	v_cvt_i32_f32_e32 v36, v36
	v_cvt_i32_f32_sdwa v38, v38 dst_sel:WORD_1 dst_unused:UNUSED_PAD src0_sel:DWORD
	v_cvt_i32_f32_e32 v39, v39
	v_lshlrev_b32_e32 v37, 8, v37
	v_and_b32_e32 v37, 0xff00, v37
	v_and_b32_e32 v38, 0xff0000, v38
	v_perm_b32 v36, v39, v36, s9
	v_or3_b32 v36, v36, v37, v38
	v_mul_f32_e32 v38, v30, v77
	v_mul_f32_e32 v37, v30, v76
	v_mul_f32_e32 v18, v30, v18
	v_mul_f32_e32 v19, v30, v19
	v_med3_f32 v38, v38, s8, v3
	v_med3_f32 v37, v37, s8, v3
	v_rndne_f32_e32 v38, v38
	v_med3_f32 v18, v18, s8, v3
	v_med3_f32 v19, v19, s8, v3
	v_rndne_f32_e32 v37, v37
	v_cvt_i32_f32_e32 v38, v38
	v_rndne_f32_e32 v18, v18
	v_rndne_f32_e32 v19, v19
	v_cvt_i32_f32_e32 v37, v37
	v_cvt_i32_f32_sdwa v18, v18 dst_sel:WORD_1 dst_unused:UNUSED_PAD src0_sel:DWORD
	v_cvt_i32_f32_e32 v19, v19
	v_lshlrev_b32_e32 v38, 8, v38
	v_and_b32_e32 v38, 0xff00, v38
	v_and_b32_e32 v18, 0xff0000, v18
	v_perm_b32 v19, v19, v37, s9
	v_or3_b32 v37, v19, v38, v18
	v_mul_f32_e32 v19, v30, v35
	v_mul_f32_e32 v18, v30, v34
	v_mul_f32_e32 v32, v30, v32
	v_mul_f32_e32 v33, v30, v33
	v_med3_f32 v19, v19, s8, v3
	v_med3_f32 v18, v18, s8, v3
	v_rndne_f32_e32 v19, v19
	v_med3_f32 v32, v32, s8, v3
	v_med3_f32 v33, v33, s8, v3
	v_rndne_f32_e32 v18, v18
	v_cvt_i32_f32_e32 v19, v19
	v_rndne_f32_e32 v32, v32
	v_rndne_f32_e32 v33, v33
	v_cvt_i32_f32_e32 v18, v18
	v_cvt_i32_f32_sdwa v32, v32 dst_sel:WORD_1 dst_unused:UNUSED_PAD src0_sel:DWORD
	v_cvt_i32_f32_e32 v33, v33
	v_lshlrev_b32_e32 v19, 8, v19
	v_and_b32_e32 v19, 0xff00, v19
	v_and_b32_e32 v32, 0xff0000, v32
	v_perm_b32 v18, v33, v18, s9
	v_or3_b32 v18, v18, v19, v32
	v_mul_f32_e32 v32, v30, v43
	v_mul_f32_e32 v19, v30, v42
	v_mul_f32_e32 v33, v30, v40
	v_mul_f32_e32 v30, v30, v41
	v_med3_f32 v32, v32, s8, v3
	v_med3_f32 v19, v19, s8, v3
	v_rndne_f32_e32 v32, v32
	v_med3_f32 v33, v33, s8, v3
	v_med3_f32 v30, v30, s8, v3
	v_rndne_f32_e32 v19, v19
	v_cvt_i32_f32_e32 v32, v32
	v_rndne_f32_e32 v33, v33
	v_rndne_f32_e32 v30, v30
	v_cvt_i32_f32_e32 v19, v19
	v_cvt_i32_f32_sdwa v33, v33 dst_sel:WORD_1 dst_unused:UNUSED_PAD src0_sel:DWORD
	v_cvt_i32_f32_e32 v30, v30
	v_lshlrev_b32_e32 v32, 8, v32
	v_and_b32_e32 v32, 0xff00, v32
	v_and_b32_e32 v33, 0xff0000, v33
	v_perm_b32 v19, v30, v19, s9
	v_or3_b32 v19, v19, v32, v33
	global_store_dwordx2 v[16:17], v[36:37], off
	global_store_dwordx2 v[16:17], v[18:19], off offset:512
	s_and_saveexec_b64 s[2:3], s[0:1]
	s_cbranch_execz .LBB0_208
	s_waitcnt lgkmcnt(0)
	v_add_f32_e32 v18, v28, v29
	v_fmamk_f32 v18, v18, 0x3a000000, v8
	v_mul_f32_e32 v19, 0x4b800000, v18
	v_cmp_gt_f32_e32 vcc, s12, v18
	global_store_dword v24, v9, s[24:25]
	s_nop 0
	v_cndmask_b32_e32 v18, v18, v19, vcc
	v_rsq_f32_e32 v18, v18
	v_mul_f32_e32 v19, 0x3c010204, v27
	v_mul_f32_e32 v27, 0x45800000, v18
	v_cndmask_b32_e32 v18, v18, v27, vcc
	v_mul_f32_e32 v18, v18, v19
	global_store_dword v9, v18, s[24:25]
	global_store_dword v25, v9, s[24:25]
	global_store_dword v26, v9, s[24:25]
	s_branch .LBB0_208

.LBB0_1904:
	s_or_b64 exec, exec, s[0:1]
	s_waitcnt lgkmcnt(0)
	v_mov_b32_e32 v0, v190
	s_barrier
	s_nop 0
	v_readfirstlane_b32 s0, v0
	s_ashr_i32 s2, s0, 6
	v_readlane_b32 s0, v251, 38
	s_add_i32 s12, s2, s0
	s_cmpk_gt_i32 s12, 0x3fff
	s_cbranch_scc1 .LBB0_1909
	v_add_u32_e32 v3, 64, v171
	v_xor_b32_e32 v4, 1, v191
	v_cmp_lt_i32_e32 vcc, v4, v3
	v_readlane_b32 s5, v251, 38
	s_ashr_i32 s3, s2, 31
	v_cndmask_b32_e32 v4, v191, v4, vcc
	v_lshlrev_b32_e32 v6, 2, v4
	v_xor_b32_e32 v4, 2, v191
	v_cmp_lt_i32_e32 vcc, v4, v3
	s_ashr_i32 s4, s5, 31
	v_readlane_b32 s16, v251, 8
	v_cndmask_b32_e32 v4, v191, v4, vcc
	v_lshlrev_b32_e32 v7, 2, v4
	v_xor_b32_e32 v4, 4, v191
	v_cmp_lt_i32_e32 vcc, v4, v3
	s_add_u32 s8, s2, s5
	v_readlane_b32 s17, v251, 9
	v_readlane_b32 s18, v251, 10
	v_readlane_b32 s19, v251, 11
	v_readlane_b32 s20, v251, 12
	v_readlane_b32 s21, v251, 13
	v_cndmask_b32_e32 v4, v191, v4, vcc
	s_addc_u32 s9, s3, s4
	v_readlane_b32 s22, v251, 14
	v_readlane_b32 s23, v251, 15
	s_mov_b64 s[16:17], s[20:21]
	v_lshlrev_b32_e32 v8, 2, v4
	v_xor_b32_e32 v4, 8, v191
	s_lshl_b64 s[2:3], s[8:9], 2
	s_mov_b64 s[18:19], s[22:23]
	v_cmp_lt_i32_e32 vcc, v4, v3
	s_add_u32 s2, s18, s2
	v_readlane_b32 s4, v252, 5
	v_cndmask_b32_e32 v4, v191, v4, vcc
	v_cmp_lt_i32_e32 vcc, v172, v3
	s_addc_u32 s3, s19, s3
	v_readlane_b32 s5, v252, 6
	s_mov_b32 s10, s4
	s_ashr_i32 s11, s4, 31
	v_lshlrev_b32_e32 v9, 2, v4
	v_cndmask_b32_e32 v4, v191, v172, vcc
	v_cmp_lt_i32_e32 vcc, v173, v3
	s_lshl_b64 s[4:5], s[10:11], 2
	s_lshl_b64 s[6:7], s[8:9], 12
	v_and_b32_e32 v2, 63, v0
	v_mov_b32_e32 v1, 0
	v_cndmask_b32_e32 v3, v191, v173, vcc
	s_add_u32 s6, s18, s6
	v_lshlrev_b32_e32 v0, 3, v2
	v_cmp_eq_u32_e64 s[0:1], 0, v2
	v_lshlrev_b32_e32 v11, 2, v3
	v_lshlrev_b32_e32 v2, 4, v2
	v_mov_b32_e32 v3, v1
	s_addc_u32 s7, s19, s7
	v_lshl_add_u64 v[2:3], s[6:7], 0, v[2:3]
	s_mov_b64 s[6:7], 0x19600800
	v_lshl_add_u64 v[2:3], v[2:3], 0, s[6:7]
	s_lshl_b64 s[6:7], s[10:11], 12
	s_lshl_b64 s[8:9], s[8:9], 11
	s_add_u32 s8, s18, s8
	s_addc_u32 s9, s19, s9
	v_lshlrev_b32_e32 v10, 2, v4
	v_lshl_add_u64 v[4:5], s[8:9], 0, v[0:1]
	s_mov_b64 s[8:9], 0xa600400
	v_lshl_add_u64 v[4:5], v[4:5], 0, s[8:9]
	s_mov_b32 s8, s10
	v_writelane_b32 v252, s8, 5
	s_mov_b32 s13, 0x42fe0000
	s_mov_b32 s14, 0xc2fe0000
	v_writelane_b32 v252, s9, 6
	s_lshl_b64 s[8:9], s[10:11], 11
	v_mov_b32_e32 v0, 0x42fe0000
	s_mov_b32 s15, 0x40c0c00
	v_mov_b32_e32 v12, 0x20000
	v_mov_b32_e32 v13, 0x358637bd
	global_load_dwordx4 v[60:63], v[2:3], off offset:-2048
	global_load_dwordx4 v[64:67], v[2:3], off offset:-1024
	global_load_dwordx4 v[68:71], v[2:3], off
	global_load_dwordx4 v[72:75], v[2:3], off offset:1024
	global_load_dword v76, v12, s[2:3]
	s_waitcnt vmcnt(0)
	s_branch .LBB0_1907

.LBB0_1907:
	s_waitcnt vmcnt(4)
	v_mov_b32_e32 v80, v60
	v_mov_b32_e32 v81, v61
	v_mov_b32_e32 v82, v62
	v_mov_b32_e32 v83, v63
	v_mov_b32_e32 v84, v64
	v_mov_b32_e32 v85, v65
	v_mov_b32_e32 v86, v66
	v_mov_b32_e32 v87, v67
	v_mov_b32_e32 v88, v68
	v_mov_b32_e32 v89, v69
	v_mov_b32_e32 v90, v70
	v_mov_b32_e32 v91, v71
	v_mov_b32_e32 v92, v72
	v_mov_b32_e32 v93, v73
	v_mov_b32_e32 v94, v74
	v_mov_b32_e32 v95, v75
	v_mov_b32_e32 v96, v76
	v_readlane_b32 vcc_lo, v252, 5
	s_add_i32 vcc_lo, s12, vcc_lo
	s_cmpk_gt_i32 vcc_lo, 0x3fff
	s_cbranch_scc1 .Lrq6_nopf
	v_lshl_add_u64 v[98:99], v[2:3], 0, s[6:7]
	global_load_dwordx4 v[60:63], v[98:99], off offset:-2048
	global_load_dwordx4 v[64:67], v[98:99], off offset:-1024
	global_load_dwordx4 v[68:71], v[98:99], off
	global_load_dwordx4 v[72:75], v[98:99], off offset:1024
	v_add_u32_e32 v100, s4, v12
	global_load_dword v76, v100, s[2:3]
.Lrq6_nopf:
	v_mov_b32_e32 v14, v80
	v_mov_b32_e32 v15, v81
	v_mov_b32_e32 v16, v82
	v_mov_b32_e32 v17, v83
	s_mov_b32 s10, 0xda24260
	v_lshlrev_b32_e32 v38, 16, v14
	v_lshlrev_b32_e32 v30, 16, v16
	v_and_b32_e32 v39, 0xffff0000, v14
	v_lshlrev_b32_e32 v40, 16, v15
	v_and_b32_e32 v41, 0xffff0000, v15
	v_and_b32_e32 v31, 0xffff0000, v16
	v_max_f32_e64 v14, |v30|, |v30|
	v_max_f32_e64 v15, |v38|, |v38|
	v_max_f32_e32 v14, v15, v14
	v_max_f32_e64 v15, |v31|, |v31|
	v_max_f32_e64 v16, |v39|, |v39|
	v_lshlrev_b32_e32 v32, 16, v17
	v_max_f32_e32 v15, v16, v15
	v_and_b32_e32 v33, 0xffff0000, v17
	v_max3_f32 v14, v14, 0, v15
	v_max_f32_e64 v15, |v32|, |v32|
	v_max_f32_e64 v16, |v40|, |v40|
	v_max_f32_e32 v15, v16, v15
	v_max_f32_e64 v16, |v33|, |v33|
	v_max_f32_e64 v17, |v41|, |v41|
	v_max_f32_e32 v16, v17, v16
	v_max3_f32 v18, v14, v15, v16
	v_mov_b32_e32 v14, v84
	v_mov_b32_e32 v15, v85
	v_mov_b32_e32 v16, v86
	v_mov_b32_e32 v17, v87
	v_lshlrev_b32_e32 v22, 16, v14
	v_and_b32_e32 v23, 0xffff0000, v14
	v_lshlrev_b32_e32 v14, 16, v16
	v_lshlrev_b32_e32 v24, 16, v15
	v_and_b32_e32 v25, 0xffff0000, v15
	v_and_b32_e32 v15, 0xffff0000, v16
	v_max_f32_e64 v19, |v14|, |v14|
	v_max_f32_e64 v20, |v22|, |v22|
	v_max_f32_e32 v19, v20, v19
	v_max_f32_e64 v20, |v15|, |v15|
	v_max_f32_e64 v21, |v23|, |v23|
	v_lshlrev_b32_e32 v16, 16, v17
	v_max_f32_e32 v20, v21, v20
	v_and_b32_e32 v17, 0xffff0000, v17
	v_max3_f32 v18, v18, v19, v20
	v_max_f32_e64 v19, |v16|, |v16|
	v_max_f32_e64 v20, |v24|, |v24|
	v_max_f32_e32 v19, v20, v19
	v_max_f32_e64 v20, |v17|, |v17|
	v_max_f32_e64 v21, |v25|, |v25|
	v_max_f32_e32 v20, v21, v20
	v_max3_f32 v34, v18, v19, v20
	v_mov_b32_e32 v18, v88
	v_mov_b32_e32 v19, v89
	v_mov_b32_e32 v20, v90
	v_mov_b32_e32 v21, v91
	v_lshlrev_b32_e32 v26, 16, v18
	v_and_b32_e32 v27, 0xffff0000, v18
	v_lshlrev_b32_e32 v18, 16, v20
	v_lshlrev_b32_e32 v28, 16, v19
	v_and_b32_e32 v29, 0xffff0000, v19
	v_and_b32_e32 v19, 0xffff0000, v20
	v_max_f32_e64 v35, |v18|, |v18|
	v_max_f32_e64 v36, |v26|, |v26|
	v_max_f32_e32 v35, v36, v35
	v_max_f32_e64 v36, |v19|, |v19|
	v_max_f32_e64 v37, |v27|, |v27|
	v_lshlrev_b32_e32 v20, 16, v21
	v_max_f32_e32 v36, v37, v36
	v_and_b32_e32 v21, 0xffff0000, v21
	v_max3_f32 v34, v34, v35, v36
	v_max_f32_e64 v35, |v20|, |v20|
	v_max_f32_e64 v36, |v28|, |v28|
	v_max_f32_e32 v35, v36, v35
	v_max_f32_e64 v36, |v21|, |v21|
	v_max_f32_e64 v37, |v29|, |v29|
	v_max_f32_e32 v36, v37, v36
	v_max3_f32 v46, v34, v35, v36
	v_mov_b32_e32 v34, v92
	v_mov_b32_e32 v35, v93
	v_mov_b32_e32 v36, v94
	v_mov_b32_e32 v37, v95
	v_lshlrev_b32_e32 v42, 16, v34
	v_and_b32_e32 v43, 0xffff0000, v34
	v_lshlrev_b32_e32 v34, 16, v36
	v_lshlrev_b32_e32 v44, 16, v35
	v_and_b32_e32 v45, 0xffff0000, v35
	v_and_b32_e32 v35, 0xffff0000, v36
	v_max_f32_e64 v47, |v34|, |v34|
	v_max_f32_e64 v48, |v42|, |v42|
	v_max_f32_e32 v47, v48, v47
	v_max_f32_e64 v48, |v35|, |v35|
	v_max_f32_e64 v49, |v43|, |v43|
	v_lshlrev_b32_e32 v36, 16, v37
	v_max_f32_e32 v48, v49, v48
	v_and_b32_e32 v37, 0xffff0000, v37
	v_max3_f32 v46, v46, v47, v48
	v_max_f32_e64 v47, |v36|, |v36|
	v_max_f32_e64 v48, |v44|, |v44|
	v_max_f32_e32 v47, v48, v47
	v_max_f32_e64 v48, |v37|, |v37|
	v_max_f32_e64 v49, |v45|, |v45|
	v_max_f32_e32 v48, v49, v48
	v_max3_f32 v46, v46, v47, v48
	ds_bpermute_b32 v47, v6, v46
	s_waitcnt lgkmcnt(0)
	v_max_f32_e32 v47, v47, v47
	v_max_f32_e32 v46, v46, v47
	ds_bpermute_b32 v47, v7, v46
	s_waitcnt lgkmcnt(0)
	v_max_f32_e32 v47, v47, v47
	v_max_f32_e32 v46, v46, v47
	ds_bpermute_b32 v47, v8, v46
	s_waitcnt lgkmcnt(0)
	v_max_f32_e32 v47, v47, v47
	v_max_f32_e32 v46, v46, v47
	ds_bpermute_b32 v47, v9, v46
	s_waitcnt lgkmcnt(0)
	v_max_f32_e32 v47, v47, v47
	v_max_f32_e32 v46, v46, v47
	ds_bpermute_b32 v47, v10, v46
	s_waitcnt lgkmcnt(0)
	v_max_f32_e32 v47, v47, v47
	v_max_f32_e32 v46, v46, v47
	ds_bpermute_b32 v47, v11, v46
	s_waitcnt lgkmcnt(0)
	v_max3_f32 v46, v46, v47, s10
	v_div_scale_f32 v47, s[10:11], v46, v46, s13
	v_rcp_f32_e32 v48, v47
	s_nop 0
	v_fma_f32 v49, -v47, v48, 1.0
	v_fmac_f32_e32 v48, v49, v48
	v_div_scale_f32 v49, vcc, s13, v46, s13
	v_mul_f32_e32 v50, v49, v48
	v_fma_f32 v51, -v47, v50, v49
	v_fmac_f32_e32 v50, v51, v48
	v_fma_f32 v47, -v47, v50, v49
	v_div_fmas_f32 v47, v47, v48, v50
	v_div_fixup_f32 v47, v47, v46, s13
	v_mul_f32_e32 v23, v47, v23
	v_mul_f32_e32 v15, v47, v15
	v_mul_f32_e32 v22, v47, v22
	v_mul_f32_e32 v24, v47, v24
	v_mul_f32_e32 v25, v47, v25
	v_med3_f32 v23, v23, s14, v0
	v_mul_f32_e32 v14, v47, v14
	v_mul_f32_e32 v16, v47, v16
	v_mul_f32_e32 v17, v47, v17
	v_med3_f32 v15, v15, s14, v0
	v_med3_f32 v22, v22, s14, v0
	v_rndne_f32_e32 v23, v23
	v_med3_f32 v24, v24, s14, v0
	v_med3_f32 v25, v25, s14, v0
	v_med3_f32 v14, v14, s14, v0
	v_rndne_f32_e32 v15, v15
	v_med3_f32 v16, v16, s14, v0
	v_med3_f32 v17, v17, s14, v0
	v_rndne_f32_e32 v22, v22
	v_cvt_i32_f32_e32 v23, v23
	v_rndne_f32_e32 v24, v24
	v_rndne_f32_e32 v25, v25
	v_rndne_f32_e32 v14, v14
	v_cvt_i32_f32_e32 v15, v15
	v_rndne_f32_e32 v16, v16
	v_rndne_f32_e32 v17, v17
	v_cvt_i32_f32_e32 v22, v22
	v_cvt_i32_f32_sdwa v24, v24 dst_sel:WORD_1 dst_unused:UNUSED_PAD src0_sel:DWORD
	v_cvt_i32_f32_e32 v25, v25
	v_cvt_i32_f32_e32 v14, v14
	v_cvt_i32_f32_sdwa v16, v16 dst_sel:WORD_1 dst_unused:UNUSED_PAD src0_sel:DWORD
	v_cvt_i32_f32_e32 v17, v17
	v_lshlrev_b32_e32 v23, 8, v23
	v_lshlrev_b32_e32 v15, 8, v15
	v_and_b32_e32 v23, 0xff00, v23
	v_and_b32_e32 v24, 0xff0000, v24
	v_perm_b32 v22, v25, v22, s15
	v_and_b32_e32 v15, 0xff00, v15
	v_and_b32_e32 v16, 0xff0000, v16
	v_perm_b32 v14, v17, v14, s15
	v_or3_b32 v22, v22, v23, v24
	v_or3_b32 v23, v14, v15, v16
	v_mul_f32_e32 v15, v47, v27
	v_mul_f32_e32 v14, v47, v26
	v_mul_f32_e32 v16, v47, v28
	v_mul_f32_e32 v17, v47, v29
	v_med3_f32 v15, v15, s14, v0
	v_med3_f32 v14, v14, s14, v0
	v_rndne_f32_e32 v15, v15
	v_med3_f32 v16, v16, s14, v0
	v_med3_f32 v17, v17, s14, v0
	v_rndne_f32_e32 v14, v14
	v_cvt_i32_f32_e32 v15, v15
	v_rndne_f32_e32 v16, v16
	v_rndne_f32_e32 v17, v17
	v_cvt_i32_f32_e32 v14, v14
	v_cvt_i32_f32_sdwa v16, v16 dst_sel:WORD_1 dst_unused:UNUSED_PAD src0_sel:DWORD
	v_cvt_i32_f32_e32 v17, v17
	v_lshlrev_b32_e32 v15, 8, v15
	v_and_b32_e32 v15, 0xff00, v15
	v_and_b32_e32 v16, 0xff0000, v16
	v_perm_b32 v14, v17, v14, s15
	v_or3_b32 v14, v14, v15, v16
	v_mul_f32_e32 v16, v47, v19
	v_mul_f32_e32 v15, v47, v18
	v_mul_f32_e32 v17, v47, v20
	v_mul_f32_e32 v18, v47, v21
	v_med3_f32 v16, v16, s14, v0
	v_med3_f32 v15, v15, s14, v0
	v_rndne_f32_e32 v16, v16
	v_med3_f32 v17, v17, s14, v0
	v_med3_f32 v18, v18, s14, v0
	v_rndne_f32_e32 v15, v15
	v_cvt_i32_f32_e32 v16, v16
	v_rndne_f32_e32 v17, v17
	v_rndne_f32_e32 v18, v18
	v_cvt_i32_f32_e32 v15, v15
	v_cvt_i32_f32_sdwa v17, v17 dst_sel:WORD_1 dst_unused:UNUSED_PAD src0_sel:DWORD
	v_cvt_i32_f32_e32 v18, v18
	v_lshlrev_b32_e32 v16, 8, v16
	v_and_b32_e32 v16, 0xff00, v16
	v_and_b32_e32 v17, 0xff0000, v17
	v_perm_b32 v15, v18, v15, s15
	v_or3_b32 v15, v15, v16, v17
	global_store_dwordx2 v[4:5], v[14:15], off
	v_mul_f32_e32 v15, v47, v43
	v_mul_f32_e32 v14, v47, v42
	v_mul_f32_e32 v16, v47, v44
	v_mul_f32_e32 v17, v47, v45
	v_med3_f32 v15, v15, s14, v0
	v_med3_f32 v14, v14, s14, v0
	v_rndne_f32_e32 v15, v15
	v_med3_f32 v16, v16, s14, v0
	v_med3_f32 v17, v17, s14, v0
	v_rndne_f32_e32 v14, v14
	v_cvt_i32_f32_e32 v15, v15
	v_rndne_f32_e32 v16, v16
	v_rndne_f32_e32 v17, v17
	v_cvt_i32_f32_e32 v14, v14
	v_cvt_i32_f32_sdwa v16, v16 dst_sel:WORD_1 dst_unused:UNUSED_PAD src0_sel:DWORD
	v_cvt_i32_f32_e32 v17, v17
	v_lshlrev_b32_e32 v15, 8, v15
	v_and_b32_e32 v15, 0xff00, v15
	v_and_b32_e32 v16, 0xff0000, v16
	v_perm_b32 v14, v17, v14, s15
	v_mul_f32_e32 v39, v47, v39
	v_mul_f32_e32 v31, v47, v31
	v_or3_b32 v14, v14, v15, v16
	v_mul_f32_e32 v16, v47, v35
	v_mul_f32_e32 v38, v47, v38
	v_mul_f32_e32 v40, v47, v40
	v_mul_f32_e32 v41, v47, v41
	v_med3_f32 v39, v39, s14, v0
	v_mul_f32_e32 v30, v47, v30
	v_mul_f32_e32 v32, v47, v32
	v_mul_f32_e32 v33, v47, v33
	v_med3_f32 v31, v31, s14, v0
	v_mul_f32_e32 v15, v47, v34
	v_mul_f32_e32 v17, v47, v36
	v_mul_f32_e32 v18, v47, v37
	v_med3_f32 v16, v16, s14, v0
	v_med3_f32 v38, v38, s14, v0
	v_rndne_f32_e32 v39, v39
	v_med3_f32 v40, v40, s14, v0
	v_med3_f32 v41, v41, s14, v0
	v_med3_f32 v30, v30, s14, v0
	v_rndne_f32_e32 v31, v31
	v_med3_f32 v32, v32, s14, v0
	v_med3_f32 v33, v33, s14, v0
	v_med3_f32 v15, v15, s14, v0
	v_rndne_f32_e32 v16, v16
	v_med3_f32 v17, v17, s14, v0
	v_med3_f32 v18, v18, s14, v0
	v_rndne_f32_e32 v38, v38
	v_cvt_i32_f32_e32 v39, v39
	v_rndne_f32_e32 v40, v40
	v_rndne_f32_e32 v41, v41
	v_rndne_f32_e32 v30, v30
	v_cvt_i32_f32_e32 v31, v31
	v_rndne_f32_e32 v32, v32
	v_rndne_f32_e32 v33, v33
	v_rndne_f32_e32 v15, v15
	v_cvt_i32_f32_e32 v16, v16
	v_rndne_f32_e32 v17, v17
	v_rndne_f32_e32 v18, v18
	v_cvt_i32_f32_e32 v38, v38
	v_cvt_i32_f32_sdwa v40, v40 dst_sel:WORD_1 dst_unused:UNUSED_PAD src0_sel:DWORD
	v_cvt_i32_f32_e32 v41, v41
	v_cvt_i32_f32_e32 v30, v30
	v_cvt_i32_f32_sdwa v32, v32 dst_sel:WORD_1 dst_unused:UNUSED_PAD src0_sel:DWORD
	v_cvt_i32_f32_e32 v33, v33
	v_cvt_i32_f32_e32 v15, v15
	v_cvt_i32_f32_sdwa v17, v17 dst_sel:WORD_1 dst_unused:UNUSED_PAD src0_sel:DWORD
	v_cvt_i32_f32_e32 v18, v18
	v_lshlrev_b32_e32 v39, 8, v39
	v_lshlrev_b32_e32 v31, 8, v31
	v_lshlrev_b32_e32 v16, 8, v16
	v_and_b32_e32 v39, 0xff00, v39
	v_and_b32_e32 v40, 0xff0000, v40
	v_perm_b32 v38, v41, v38, s15
	v_and_b32_e32 v31, 0xff00, v31
	v_and_b32_e32 v32, 0xff0000, v32
	v_perm_b32 v30, v33, v30, s15
	v_and_b32_e32 v16, 0xff00, v16
	v_and_b32_e32 v17, 0xff0000, v17
	v_perm_b32 v15, v18, v15, s15
	v_or3_b32 v38, v38, v39, v40
	v_or3_b32 v39, v30, v31, v32
	v_or3_b32 v15, v15, v16, v17
	global_store_dwordx2 v[4:5], v[38:39], off offset:-1024
	global_store_dwordx2 v[4:5], v[22:23], off offset:-512
	global_store_dwordx2 v[4:5], v[14:15], off offset:512
	s_and_saveexec_b64 s[10:11], s[0:1]
	s_cbranch_execz .LBB0_1906
	v_mov_b32_e32 v14, v96
	s_mov_b32 s16, 0x800000
	v_fmamk_f32 v14, v14, 0x3a000000, v13
	v_mul_f32_e32 v15, 0x4b800000, v14
	v_cmp_gt_f32_e32 vcc, s16, v14
	s_nop 1
	v_cndmask_b32_e32 v14, v14, v15, vcc
	v_rsq_f32_e32 v14, v14
	v_mul_f32_e32 v15, 0x3c010204, v46
	v_mul_f32_e32 v16, 0x45800000, v14
	v_cndmask_b32_e32 v14, v14, v16, vcc
	v_mul_f32_e32 v14, v15, v14
	global_store_dword v1, v14, s[2:3]
	s_branch .LBB0_1906
